# attention loop 1: first-half K/V prefetch-issue block moved after the next tile's LDS fragment reads (overlaps scalar address setup with LDS latency)
# speedup vs baseline: 1.0116x; 1.0116x over previous
.LBB0_1368:
	s_cbranch_execz .LBB0_1371
.LBB0_1369:
	s_branch .LBB0_1374
.LBB0_1370:
	s_andn2_b64 vcc, exec, s[2:3]
	s_cbranch_vccnz .LBB0_1369

.LBB0_1374:
	s_add_i32 s2, s28, -2
	s_and_b32 s2, s2, 3
	s_mulk_i32 s2, 0x3000
	v_add_u32_e32 v52, s2, v180
	ds_read_b128 v[48:51], v52
	ds_read_b128 v[184:187], v52 offset:512
	ds_read_b128 v[204:207], v52 offset:2048
	ds_read_b128 v[208:211], v52 offset:2560
	ds_read_b128 v[218:221], v52 offset:4096
	ds_read_b128 v[222:225], v52 offset:4608
	ds_read_b128 v[226:229], v52 offset:6144
	ds_read_b128 v[230:233], v52 offset:6656
	s_add_i32 s2, s75, 0xffffa000
	s_and_b32 s2, s2, 0x6000
	v_add_f32_e32 v52, v96, v97
	v_add_u32_e32 v203, s2, v199
	ds_read_b64_tr_b16 v[176:177], v203 offset:49152
	ds_read_b64_tr_b16 v[178:179], v203 offset:49664
	s_and_b64 vcc, exec, s[6:7]
	s_cbranch_vccnz .Latt1_nopf
	s_cmp_ge_i32 s28, s69
	s_cbranch_scc1 .Latt1_nopf
	s_cmp_gt_u32 s29, 4
	s_cselect_b32 s2, s77, 0
	s_add_i32 s2, s2, s28
	s_lshl_b32 s2, s2, 6
	s_add_i32 s2, s2, s72
	s_mul_hi_i32 s3, s2, s39
	s_mul_i32 s2, s2, s39
	s_lshl_b64 s[2:3], s[2:3], 1
	s_and_b32 s50, s28, 3
	v_lshl_add_u64 v[54:55], v[190:191], 0, s[2:3]
	s_mul_i32 s51, s50, 0x3000
	s_add_i32 s51, s51, s87
	s_mov_b32 s55, m0
	s_mov_b32 m0, s51
	s_nop 0
	global_load_lds_dwordx4 v[54:55], off
	s_mov_b32 m0, s55
	v_lshl_add_u64 v[54:55], v[114:115], 0, s[2:3]
	s_lshl_b32 s2, s50, 13
	s_add_i32 s2, s2, s83
	s_mov_b32 s3, m0
	s_mov_b32 m0, s2
	s_nop 0
	global_load_lds_dwordx4 v[54:55], off
	s_mov_b32 m0, s3
.Latt1_nopf:
	s_waitcnt lgkmcnt(9)
	v_mfma_f32_32x32x16_bf16 v[64:79], v[48:51], v[168:171], v[32:47]
	v_add_f32_e32 v52, v98, v52
	v_add_f32_e32 v52, v99, v52
	v_add_f32_e32 v52, v100, v52
	v_add_f32_e32 v52, v101, v52
	v_cvt_pk_bf16_f32 v148, v96, v97
	v_cvt_pk_bf16_f32 v149, v98, v99
	ds_read_b64_tr_b16 v[172:173], v203 offset:53248
	ds_read_b64_tr_b16 v[174:175], v203 offset:53760
	v_add_f32_e32 v48, v102, v52
	v_add_f32_e32 v48, v103, v48
	v_add_f32_e32 v48, v104, v48
	v_add_f32_e32 v140, v105, v48
	s_waitcnt lgkmcnt(10)
	v_mfma_f32_32x32x16_bf16 v[48:63], v[184:187], v[168:171], v[32:47]
	v_cvt_pk_bf16_f32 v150, v100, v101
	v_cvt_pk_bf16_f32 v151, v102, v103
	ds_read_b64_tr_b16 v[96:97], v203 offset:50176
	ds_read_b64_tr_b16 v[98:99], v203 offset:50688
	s_waitcnt lgkmcnt(11)
	v_mfma_f32_32x32x16_bf16 v[64:79], v[204:207], v[164:167], v[64:79]
	v_add_f32_e32 v100, v106, v140
	v_add_f32_e32 v100, v107, v100
	v_add_f32_e32 v100, v108, v100
	v_add_f32_e32 v140, v109, v100
	v_cvt_pk_bf16_f32 v152, v104, v105
	v_cvt_pk_bf16_f32 v153, v106, v107
	ds_read_b64_tr_b16 v[100:101], v203 offset:54272
	ds_read_b64_tr_b16 v[102:103], v203 offset:54784
	s_waitcnt lgkmcnt(12)
	v_mfma_f32_32x32x16_bf16 v[48:63], v[208:211], v[164:167], v[48:63]
	v_add_f32_e32 v104, v110, v140
	v_add_f32_e32 v104, v111, v104
	v_add_f32_e32 v104, v80, v104
	v_add_f32_e32 v140, v81, v104
	v_cvt_pk_bf16_f32 v154, v108, v109
	v_cvt_pk_bf16_f32 v155, v110, v111
	ds_read_b64_tr_b16 v[104:105], v203 offset:51200
	ds_read_b64_tr_b16 v[106:107], v203 offset:51712
	s_waitcnt lgkmcnt(13)
	v_mfma_f32_32x32x16_bf16 v[64:79], v[218:221], v[160:163], v[64:79]
	v_add_f32_e32 v108, v82, v140
	v_add_f32_e32 v108, v83, v108
	v_add_f32_e32 v108, v84, v108
	v_add_f32_e32 v108, v85, v108
	v_cvt_pk_bf16_f32 v144, v80, v81
	v_cvt_pk_bf16_f32 v145, v82, v83
	ds_read_b64_tr_b16 v[80:81], v203 offset:55296
	ds_read_b64_tr_b16 v[82:83], v203 offset:55808
	s_waitcnt lgkmcnt(14)
	v_mfma_f32_32x32x16_bf16 v[48:63], v[222:225], v[160:163], v[48:63]
	v_add_f32_e32 v108, v86, v108
	v_add_f32_e32 v108, v87, v108
	v_add_f32_e32 v108, v88, v108
	v_add_f32_e32 v108, v89, v108
	v_cvt_pk_bf16_f32 v146, v84, v85
	v_cvt_pk_bf16_f32 v147, v86, v87
	ds_read_b64_tr_b16 v[84:85], v203 offset:52224
	ds_read_b64_tr_b16 v[86:87], v203 offset:52736
	s_waitcnt lgkmcnt(14)
	v_mfma_f32_32x32x16_bf16 v[64:79], v[226:229], v[156:159], v[64:79]
	v_add_f32_e32 v108, v90, v108
	v_add_f32_e32 v108, v91, v108
	v_add_f32_e32 v108, v92, v108
	v_add_f32_e32 v108, v93, v108
	v_cvt_pk_bf16_f32 v140, v88, v89
	v_cvt_pk_bf16_f32 v141, v90, v91
	ds_read_b64_tr_b16 v[88:89], v203 offset:56320
	ds_read_b64_tr_b16 v[90:91], v203 offset:56832
	v_mfma_f32_32x32x16_bf16 v[48:63], v[230:233], v[156:159], v[48:63]
	v_add_f32_e32 v108, v94, v108
	v_add_f32_e32 v108, v95, v108
	v_cvt_pk_bf16_f32 v142, v92, v93
	v_cvt_pk_bf16_f32 v143, v94, v95
	s_cmp_gt_u32 s29, 6
	s_cselect_b64 s[2:3], -1, 0
	s_and_b64 s[2:3], s[48:49], s[2:3]
	s_add_i32 s54, s54, -12
	s_cmp_lt_u32 s54, -3
	s_cselect_b64 s[50:51], -1, 0
	s_and_b64 s[2:3], s[2:3], s[50:51]
	s_andn2_b64 vcc, exec, s[2:3]
	s_cbranch_vccnz .LBB0_1376
	v_add_u32_e32 v92, 64, v182
	v_cmp_lt_u32_e32 vcc, s78, v92
	v_add_u32_e32 v92, 0x60, v182
	s_nop 0
	v_cndmask_b32_e32 v64, v253, v64, vcc
	v_cmp_lt_u32_e32 vcc, s78, v92
	v_add_u32_e32 v92, 0x41, v182
	s_nop 0
	v_cndmask_b32_e32 v48, v253, v48, vcc
	v_cmp_lt_u32_e32 vcc, s78, v92
	v_add_u32_e32 v92, 0x61, v182
	s_nop 0
	v_cndmask_b32_e32 v65, v253, v65, vcc
	v_cmp_lt_u32_e32 vcc, s78, v92
	v_add_u32_e32 v92, 0x42, v182
	s_nop 0
	v_cndmask_b32_e32 v49, v253, v49, vcc
	v_cmp_lt_u32_e32 vcc, s78, v92
	v_add_u32_e32 v92, 0x62, v182
	s_nop 0
	v_cndmask_b32_e32 v66, v253, v66, vcc
	v_cmp_lt_u32_e32 vcc, s78, v92
	v_add_u32_e32 v92, 0x43, v182
	s_nop 0
	v_cndmask_b32_e32 v50, v253, v50, vcc
	v_cmp_lt_u32_e32 vcc, s78, v92
	v_add_u32_e32 v92, 0x63, v182
	s_nop 0
	v_cndmask_b32_e32 v67, v253, v67, vcc
	v_cmp_lt_u32_e32 vcc, s78, v92
	v_add_u32_e32 v92, 0x48, v182
	s_nop 0
	v_cndmask_b32_e32 v51, v253, v51, vcc
	v_cmp_lt_u32_e32 vcc, s78, v92
	v_add_u32_e32 v92, 0x68, v182
	s_nop 0
	v_cndmask_b32_e32 v68, v253, v68, vcc
	v_cmp_lt_u32_e32 vcc, s78, v92
	v_add_u32_e32 v92, 0x49, v182
	s_nop 0
	v_cndmask_b32_e32 v52, v253, v52, vcc
	v_cmp_lt_u32_e32 vcc, s78, v92
	v_add_u32_e32 v92, 0x69, v182
	s_nop 0
	v_cndmask_b32_e32 v69, v253, v69, vcc
	v_cmp_lt_u32_e32 vcc, s78, v92
	v_add_u32_e32 v92, 0x4a, v182
	s_nop 0
	v_cndmask_b32_e32 v53, v253, v53, vcc
	v_cmp_lt_u32_e32 vcc, s78, v92
	v_add_u32_e32 v92, 0x6a, v182
	s_nop 0
	v_cndmask_b32_e32 v70, v253, v70, vcc
	v_cmp_lt_u32_e32 vcc, s78, v92
	v_add_u32_e32 v92, 0x4b, v182
	s_nop 0
	v_cndmask_b32_e32 v54, v253, v54, vcc
	v_cmp_lt_u32_e32 vcc, s78, v92
	v_add_u32_e32 v92, 0x6b, v182
	s_nop 0
	v_cndmask_b32_e32 v71, v253, v71, vcc
	v_cmp_lt_u32_e32 vcc, s78, v92
	v_add_u32_e32 v92, 0x50, v182
	s_nop 0
	v_cndmask_b32_e32 v55, v253, v55, vcc
	v_cmp_lt_u32_e32 vcc, s78, v92
	v_add_u32_e32 v92, 0x70, v182
	s_nop 0
	v_cndmask_b32_e32 v72, v253, v72, vcc
	v_cmp_lt_u32_e32 vcc, s78, v92
	v_add_u32_e32 v92, 0x51, v182
	s_nop 0
	v_cndmask_b32_e32 v56, v253, v56, vcc
	v_cmp_lt_u32_e32 vcc, s78, v92
	v_add_u32_e32 v92, 0x71, v182
	s_nop 0
	v_cndmask_b32_e32 v73, v253, v73, vcc
	v_cmp_lt_u32_e32 vcc, s78, v92
	v_add_u32_e32 v92, 0x52, v182
	s_nop 0
	v_cndmask_b32_e32 v57, v253, v57, vcc
	v_cmp_lt_u32_e32 vcc, s78, v92
	v_add_u32_e32 v92, 0x72, v182
	s_nop 0
	v_cndmask_b32_e32 v74, v253, v74, vcc
	v_cmp_lt_u32_e32 vcc, s78, v92
	v_add_u32_e32 v92, 0x53, v182
	s_nop 0
	v_cndmask_b32_e32 v58, v253, v58, vcc
	v_cmp_lt_u32_e32 vcc, s78, v92
	v_add_u32_e32 v92, 0x73, v182
	s_nop 0
	v_cndmask_b32_e32 v75, v253, v75, vcc
	v_cmp_lt_u32_e32 vcc, s78, v92
	v_add_u32_e32 v92, 0x58, v182
	s_nop 0
	v_cndmask_b32_e32 v59, v253, v59, vcc
	v_cmp_lt_u32_e32 vcc, s78, v92
	v_add_u32_e32 v92, 0x78, v182
	s_nop 0
	v_cndmask_b32_e32 v76, v253, v76, vcc
	v_cmp_lt_u32_e32 vcc, s78, v92
	v_add_u32_e32 v92, 0x59, v182
	s_nop 0
	v_cndmask_b32_e32 v60, v253, v60, vcc
	v_cmp_lt_u32_e32 vcc, s78, v92
	v_add_u32_e32 v92, 0x79, v182
	s_nop 0
	v_cndmask_b32_e32 v77, v253, v77, vcc
	v_cmp_lt_u32_e32 vcc, s78, v92
	v_add_u32_e32 v92, 0x5a, v182
	s_nop 0
	v_cndmask_b32_e32 v61, v253, v61, vcc
	v_cmp_lt_u32_e32 vcc, s78, v92
	v_add_u32_e32 v92, 0x7a, v182
	s_nop 0
	v_cndmask_b32_e32 v78, v253, v78, vcc
	v_cmp_lt_u32_e32 vcc, s78, v92
	v_add_u32_e32 v92, 0x5b, v182
	s_nop 0
	v_cndmask_b32_e32 v62, v253, v62, vcc
	v_cmp_lt_u32_e32 vcc, s78, v92
	v_add_u32_e32 v92, 0x7b, v182
	s_nop 0
	v_cndmask_b32_e32 v79, v253, v79, vcc
	v_cmp_lt_u32_e32 vcc, s78, v92
	s_nop 1
	v_cndmask_b32_e32 v63, v253, v63, vcc
